# v28 plus phase-3 tail rebalance: the ret_out mini-GEMM runs on blocks 64..127 instead of 0..63 so its tail overlaps the swa_out mini-GEMM tail
# speedup vs baseline: 1.0194x; 1.0194x over previous
; template <class Epi>
; DI void mini_gemm_phase(lptr L, const pg8::Gemm g, const int row_base, const Epi& E) {
;     const int tid = threadIdx.x, wid = __builtin_amdgcn_readfirstlane(tid >> 6), lane = tid & 63, kh = wid >> 2, wc = wid & 3, fr = lane & 15, fq = lane >> 4;
;     const int nN = g.N / 256, nItems = (g.M / 64) * nN, G = gridDim.x, nt = g.K / 64;
;     constexpr int PB = 144, ST_A = 0, ST_B = 9216, ST_SZ = 46080;
;     const int arow = tid >> 3, ach = tid & 7;
;     for (int it = blockIdx.x; it < nItems; it += G) {
;         const int im = it / nN, in = it % nN;
;         const bf16_t* Ab = g.A + (size_t)(im * 64 + arow) * g.lda + ach * 8;
;         const bf16_t* Bb = g.Bt + (size_t)(in * 256 + arow) * g.K + ach * 8;
;         u32x4 ra[4], rb[4][4];
; __global__ void __launch_bounds__(512, 2) fwd_mega(Params p) {
;     ...
;         pg8::Gemm gs{P + G_RV + (size_t)MP * DM, DM, (const bf16_t*)(ws + WS_WRO), MS, DM, DM}; mini_gemm_phase<EpiRetOut>(L, gs, MP, E);
.LBB0_759:
	s_mov_b32 s98, s64
	s_cmpk_lg_i32 s65, 0x100
	s_cbranch_scc1 .Lm2_keep
	s_add_i32 s98, s64, 0xffffffc0
.Lm2_keep:
	s_cmp_lt_u32 s98, 64
	s_cselect_b64 s[8:9], -1, 0
	s_andn2_b64 vcc, exec, s[8:9]
	v_readfirstlane_b32 s4, v153
	s_cbranch_vccnz .LBB0_778
	v_and_b32_e32 v0, 7, v153
	v_lshlrev_b32_e32 v2, 4, v0
	v_mov_b32_e32 v0, 0
	s_lshr_b32 s9, s4, 8
	v_mov_b32_e32 v3, v0
	s_lshr_b32 s8, s4, 6
	s_bfe_u32 s5, s4, 0x20006
	v_lshl_add_u64 v[158:159], s[0:1], 0, v[2:3]
	s_lshl_b32 s1, s9, 6
	v_lshl_add_u64 v[154:155], s[94:95], 0, v[2:3]
	s_mov_b64 s[2:3], 0x1b400000
	v_lshlrev_b32_e32 v3, 1, v153
	s_cmp_eq_u32 s9, 1
	v_lshl_add_u64 v[156:157], v[154:155], 0, s[2:3]
	v_and_b32_e32 v3, 24, v3
	s_cselect_b64 s[2:3], -1, 0
	s_lshl_b32 s16, s5, 14
	v_and_or_b32 v3, v153, 3, v3
	s_cmpk_lt_u32 s4, 0x100
	v_lshl_or_b32 v3, s5, 5, v3
	s_cselect_b64 s[4:5], -1, 0
	s_lshl_b32 s17, s8, 14
	v_lshl_or_b32 v188, s8, 5, v177
	s_add_u32 s8, s94, 0x2da80000
	s_movk_i32 s0, 0x90
	v_and_b32_e32 v1, 48, v153
	v_and_b32_e32 v4, 0x3f0, v176
	s_addc_u32 s9, s95, 0
	v_add_u32_e32 v189, 0, v2
	s_add_i32 s1, s1, 0
	v_mov_b32_e32 v7, 0x4800
	v_mov_b32_e32 v8, 0x4a40
	v_mul_u32_u24_e32 v186, 0x90, v184
	v_add_u32_e32 v187, 0, v4
	v_mad_u32_u24 v4, v184, s0, 0
	v_add_u32_e32 v1, s1, v1
	v_mul_u32_u24_e32 v5, 0x90, v178
	v_mul_u32_u24_e32 v6, 0x90, v3
	v_mad_u32_u24 v7, v3, s0, v7
	v_mad_u32_u24 v3, v3, s0, v8
	v_add_u32_e32 v8, 0xd800, v189
	s_mov_b64 s[0:1], 0x1b400300
	v_lshl_add_u64 v[160:161], v[154:155], 0, s[0:1]
	s_mov_b32 s18, 0x20000
	s_mov_b32 s19, 0x40000
	s_mov_b32 s20, 0x60000
	v_mov_b32_e32 v190, 0x358637bd
	s_mov_b32 s21, 0x8200000
	s_mov_b32 s22, 0x2aa80000
	v_add_u32_e32 v191, v4, v2
	v_add_u32_e32 v192, v1, v5
	v_add_u32_e32 v193, v1, v6
	v_add_u32_e32 v194, v8, v186
	v_add_u32_e32 v195, v1, v7
	v_add_u32_e32 v196, v1, v3
	s_mov_b32 s23, s98
	s_branch .LBB0_762
